# barrier elimination: route_b items re-mapped to the wave that gathers those tokens, last grid barrier (route_b -> gather) removed
# speedup vs baseline: 1.0039x; 1.0039x over previous
.LBB0_1003:
	s_or_b64 exec, exec, s[0:1]
	s_mov_b64 s[0:1], 0x40000
	v_cmp_gt_u64_e32 vcc, s[0:1], v[134:135]
	s_waitcnt lgkmcnt(0)
	s_barrier
	s_and_saveexec_b64 s[10:11], vcc
	s_cbranch_execz .LBB0_1006
	s_add_u32 s12, s74, 0x3000000
	s_addc_u32 s13, s75, 0
	v_readlane_b32 s2, v247, 0
	s_add_u32 s14, s74, 0x5000000
	v_readlane_b32 s3, v247, 1
	s_addc_u32 s15, s75, 0
	s_lshl_b64 s[0:1], s[2:3], 14
	s_add_u32 s0, s74, s0
	v_lshlrev_b64 v[0:1], 6, v[130:131]
	s_addc_u32 s1, s75, s1
	v_lshl_add_u64 v[0:1], s[0:1], 0, v[0:1]
	s_mov_b64 s[0:1], 0x2000000
	v_readlane_b32 s4, v246, 30
	v_lshl_add_u64 v[24:25], v[0:1], 0, s[0:1]
	v_readlane_b32 s5, v246, 31
	s_lshl_b64 s[0:1], s[2:3], 12
	s_lshl_b64 s[16:17], s[4:5], 14
	v_lshl_add_u64 v[26:27], v[130:131], 4, s[0:1]
	s_lshl_b64 s[18:19], s[4:5], 12
	s_mov_b64 s[20:21], 0
	s_mov_b64 s[22:23], 0x1000000
	s_mov_b32 s4, 0x1000000
	s_movk_i32 s5, 0xff00
	v_mov_b32_e32 v29, 0
	s_mov_b32 s26, 0xf149f2ca
	s_mov_b32 s27, 0xfe000000
	s_mov_b32 s28, 0xff000000
	s_mov_b32 s29, 0xfe001000
	s_mov_b32 s30, 0xff001000
	s_mov_b64 s[24:25], 0x3ffff
	v_and_b32_e32 v0, 7, v128
	v_lshrrev_b32_e32 v1, 3, v128
	v_lshl_add_u32 v0, v132, 3, v0
	v_lshl_add_u32 v0, v1, 14, v0
	v_mov_b32_e32 v1, 0
	s_add_u32 s0, s74, 0x2000000
	s_addc_u32 s1, s75, 0
	v_mov_b64_e32 v[134:135], v[0:1]
	v_lshlrev_b64 v[26:27], 4, v[0:1]
	v_lshlrev_b64 v[24:25], 6, v[0:1]
	s_nop 0
	v_lshl_add_u64 v[24:25], v[24:25], 0, s[0:1]

.LBB0_1006:
	s_or_b64 exec, exec, s[10:11]
	s_waitcnt vmcnt(0)
	s_mov_b64 s[0:1], exec
